# mod GEMV: first 47 weight rows requested before the c wait and the silu
# baseline (speedup 1.0000x reference)
.LBB0_5:
	s_or_b64 exec, exec, s[4:5]
	s_load_dwordx16 s[36:51], s[0:1], 0x0
	s_add_u32 s68, s26, 0x100000
	s_addc_u32 s69, s27, 0
	s_cmpk_gt_i32 s2, 0xbf
	v_and_b32_e32 v120, 31, v0
	s_cbranch_scc1 .LBB0_17
	s_waitcnt lgkmcnt(0)
	s_mov_b32 s4, s2
	v_lshrrev_b32_e32 v1, 6, v0
	v_and_b32_e32 v2, 63, v0
	s_mov_b32 s16, 0xbfb8aa3b
	v_readfirstlane_b32 s5, v1
	s_mov_b32 s17, 0x42ce8ed0
	s_mov_b32 s20, 0xc2b17218
	v_mov_b32_e32 v7, 0x7f800000
	v_and_b32_e32 v3, 31, v2
	v_lshrrev_b32_e32 v4, 5, v2
	v_lshlrev_b32_e32 v5, 12, v3
	v_lshl_add_u32 v5, v4, 8, v5
	s_lshl_b32 s6, s5, 9
	v_add_u32_e32 v5, s6, v5
	v_mul_u32_u24_e32 v6, 0x180000, v4
	v_lshl_add_u32 v6, v3, 2, v6
	global_load_dwordx4 v[8:11], v5, s[38:39]
	global_load_dwordx4 v[12:15], v5, s[38:39] offset:16
	global_load_dwordx4 v[16:19], v5, s[38:39] offset:32
	global_load_dwordx4 v[20:23], v5, s[38:39] offset:48
	global_load_dwordx4 v[24:27], v5, s[38:39] offset:64
	global_load_dwordx4 v[28:31], v5, s[38:39] offset:80
	global_load_dwordx4 v[32:35], v5, s[38:39] offset:96
	global_load_dwordx4 v[36:39], v5, s[38:39] offset:112
	global_load_dwordx4 v[40:43], v5, s[38:39] offset:128
	global_load_dwordx4 v[44:47], v5, s[38:39] offset:144
	global_load_dwordx4 v[48:51], v5, s[38:39] offset:160
	global_load_dwordx4 v[52:55], v5, s[38:39] offset:176
	global_load_dwordx4 v[56:59], v5, s[38:39] offset:192
	global_load_dwordx4 v[60:63], v5, s[38:39] offset:208
	global_load_dwordx4 v[64:67], v5, s[38:39] offset:224
	global_load_dwordx4 v[68:71], v5, s[38:39] offset:240
	s_mul_i32 s6, s5, 0x300000
	s_lshl_b32 s7, s4, 7
	s_add_u32 s6, s6, s7
	s_add_u32 s8, s40, s6
	s_addc_u32 s9, s41, 0
	global_load_dword v130, v6, s[8:9]
	s_add_u32 s8, s8, 0x6000
	s_addc_u32 s9, s9, 0
	global_load_dword v131, v6, s[8:9]
	s_add_u32 s8, s8, 0x6000
	s_addc_u32 s9, s9, 0
	global_load_dword v132, v6, s[8:9]
	s_add_u32 s8, s8, 0x6000
	s_addc_u32 s9, s9, 0
	global_load_dword v133, v6, s[8:9]
	s_add_u32 s8, s8, 0x6000
	s_addc_u32 s9, s9, 0
	global_load_dword v134, v6, s[8:9]
	s_add_u32 s8, s8, 0x6000
	s_addc_u32 s9, s9, 0
	global_load_dword v135, v6, s[8:9]
	s_add_u32 s8, s8, 0x6000
	s_addc_u32 s9, s9, 0
	global_load_dword v136, v6, s[8:9]
	s_add_u32 s8, s8, 0x6000
	s_addc_u32 s9, s9, 0
	global_load_dword v137, v6, s[8:9]
	s_add_u32 s8, s8, 0x6000
	s_addc_u32 s9, s9, 0
	global_load_dword v138, v6, s[8:9]
	s_add_u32 s8, s8, 0x6000
	s_addc_u32 s9, s9, 0
	global_load_dword v139, v6, s[8:9]
	s_add_u32 s8, s8, 0x6000
	s_addc_u32 s9, s9, 0
	global_load_dword v140, v6, s[8:9]
	s_add_u32 s8, s8, 0x6000
	s_addc_u32 s9, s9, 0
	global_load_dword v141, v6, s[8:9]
	s_add_u32 s8, s8, 0x6000
	s_addc_u32 s9, s9, 0
	global_load_dword v142, v6, s[8:9]
	s_add_u32 s8, s8, 0x6000
	s_addc_u32 s9, s9, 0
	global_load_dword v143, v6, s[8:9]
	s_add_u32 s8, s8, 0x6000
	s_addc_u32 s9, s9, 0
	global_load_dword v144, v6, s[8:9]
	s_add_u32 s8, s8, 0x6000
	s_addc_u32 s9, s9, 0
	global_load_dword v145, v6, s[8:9]
	s_add_u32 s8, s8, 0x6000
	s_addc_u32 s9, s9, 0
	global_load_dword v146, v6, s[8:9]
	s_add_u32 s8, s8, 0x6000
	s_addc_u32 s9, s9, 0
	global_load_dword v147, v6, s[8:9]
	s_add_u32 s8, s8, 0x6000
	s_addc_u32 s9, s9, 0
	global_load_dword v148, v6, s[8:9]
	s_add_u32 s8, s8, 0x6000
	s_addc_u32 s9, s9, 0
	global_load_dword v149, v6, s[8:9]
	s_add_u32 s8, s8, 0x6000
	s_addc_u32 s9, s9, 0
	global_load_dword v150, v6, s[8:9]
	s_add_u32 s8, s8, 0x6000
	s_addc_u32 s9, s9, 0
	global_load_dword v151, v6, s[8:9]
	s_add_u32 s8, s8, 0x6000
	s_addc_u32 s9, s9, 0
	global_load_dword v152, v6, s[8:9]
	s_add_u32 s8, s8, 0x6000
	s_addc_u32 s9, s9, 0
	global_load_dword v153, v6, s[8:9]
	s_add_u32 s8, s8, 0x6000
	s_addc_u32 s9, s9, 0
	global_load_dword v154, v6, s[8:9]
	s_add_u32 s8, s8, 0x6000
	s_addc_u32 s9, s9, 0
	global_load_dword v155, v6, s[8:9]
	s_add_u32 s8, s8, 0x6000
	s_addc_u32 s9, s9, 0
	global_load_dword v156, v6, s[8:9]
	s_add_u32 s8, s8, 0x6000
	s_addc_u32 s9, s9, 0
	global_load_dword v157, v6, s[8:9]
	s_add_u32 s8, s8, 0x6000
	s_addc_u32 s9, s9, 0
	global_load_dword v158, v6, s[8:9]
	s_add_u32 s8, s8, 0x6000
	s_addc_u32 s9, s9, 0
	global_load_dword v159, v6, s[8:9]
	s_add_u32 s8, s8, 0x6000
	s_addc_u32 s9, s9, 0
	global_load_dword v160, v6, s[8:9]
	s_add_u32 s8, s8, 0x6000
	s_addc_u32 s9, s9, 0
	global_load_dword v161, v6, s[8:9]
	s_add_u32 s8, s8, 0x6000
	s_addc_u32 s9, s9, 0
	global_load_dword v162, v6, s[8:9]
	s_add_u32 s8, s8, 0x6000
	s_addc_u32 s9, s9, 0
	global_load_dword v163, v6, s[8:9]
	s_add_u32 s8, s8, 0x6000
	s_addc_u32 s9, s9, 0
	global_load_dword v164, v6, s[8:9]
	s_add_u32 s8, s8, 0x6000
	s_addc_u32 s9, s9, 0
	global_load_dword v165, v6, s[8:9]
	s_add_u32 s8, s8, 0x6000
	s_addc_u32 s9, s9, 0
	global_load_dword v166, v6, s[8:9]
	s_add_u32 s8, s8, 0x6000
	s_addc_u32 s9, s9, 0
	global_load_dword v167, v6, s[8:9]
	s_add_u32 s8, s8, 0x6000
	s_addc_u32 s9, s9, 0
	global_load_dword v168, v6, s[8:9]
	s_add_u32 s8, s8, 0x6000
	s_addc_u32 s9, s9, 0
	global_load_dword v169, v6, s[8:9]
	s_add_u32 s8, s8, 0x6000
	s_addc_u32 s9, s9, 0
	global_load_dword v170, v6, s[8:9]
	s_add_u32 s8, s8, 0x6000
	s_addc_u32 s9, s9, 0
	global_load_dword v171, v6, s[8:9]
	s_add_u32 s8, s8, 0x6000
	s_addc_u32 s9, s9, 0
	global_load_dword v172, v6, s[8:9]
	s_add_u32 s8, s8, 0x6000
	s_addc_u32 s9, s9, 0
	global_load_dword v173, v6, s[8:9]
	s_add_u32 s8, s8, 0x6000
	s_addc_u32 s9, s9, 0
	global_load_dword v174, v6, s[8:9]
	s_add_u32 s8, s8, 0x6000
	s_addc_u32 s9, s9, 0
	global_load_dword v175, v6, s[8:9]
	s_add_u32 s8, s8, 0x6000
	s_addc_u32 s9, s9, 0
	global_load_dword v176, v6, s[8:9]
	s_add_u32 s8, s8, 0x6000
	s_addc_u32 s9, s9, 0
	s_waitcnt vmcnt(47)
	v_mul_f32_e32 v72, 0xbfb8aa3b, v8
	v_mul_f32_e32 v73, 0xbfb8aa3b, v9
	v_mul_f32_e32 v74, 0xbfb8aa3b, v10
	v_mul_f32_e32 v75, 0xbfb8aa3b, v11
	v_mul_f32_e32 v76, 0xbfb8aa3b, v12
	v_mul_f32_e32 v77, 0xbfb8aa3b, v13
	v_mul_f32_e32 v78, 0xbfb8aa3b, v14
	v_mul_f32_e32 v79, 0xbfb8aa3b, v15
	v_exp_f32_e32 v72, v72
	v_exp_f32_e32 v73, v73
	v_exp_f32_e32 v74, v74
	v_exp_f32_e32 v75, v75
	v_exp_f32_e32 v76, v76
	v_exp_f32_e32 v77, v77
	v_exp_f32_e32 v78, v78
	v_exp_f32_e32 v79, v79
	v_add_f32_e32 v72, 1.0, v72
	v_add_f32_e32 v73, 1.0, v73
	v_add_f32_e32 v74, 1.0, v74
	v_add_f32_e32 v75, 1.0, v75
	v_add_f32_e32 v76, 1.0, v76
	v_add_f32_e32 v77, 1.0, v77
	v_add_f32_e32 v78, 1.0, v78
	v_add_f32_e32 v79, 1.0, v79
	v_rcp_f32_e32 v72, v72
	v_rcp_f32_e32 v73, v73
	v_rcp_f32_e32 v74, v74
	v_rcp_f32_e32 v75, v75
	v_rcp_f32_e32 v76, v76
	v_rcp_f32_e32 v77, v77
	v_rcp_f32_e32 v78, v78
	v_rcp_f32_e32 v79, v79
	v_mul_f32_e32 v8, v8, v72
	v_mul_f32_e32 v9, v9, v73
	v_mul_f32_e32 v10, v10, v74
	v_mul_f32_e32 v11, v11, v75
	v_mul_f32_e32 v12, v12, v76
	v_mul_f32_e32 v13, v13, v77
	v_mul_f32_e32 v14, v14, v78
	v_mul_f32_e32 v15, v15, v79
	v_mul_f32_e32 v72, 0xbfb8aa3b, v16
	v_mul_f32_e32 v73, 0xbfb8aa3b, v17
	v_mul_f32_e32 v74, 0xbfb8aa3b, v18
	v_mul_f32_e32 v75, 0xbfb8aa3b, v19
	v_mul_f32_e32 v76, 0xbfb8aa3b, v20
	v_mul_f32_e32 v77, 0xbfb8aa3b, v21
	v_mul_f32_e32 v78, 0xbfb8aa3b, v22
	v_mul_f32_e32 v79, 0xbfb8aa3b, v23
	v_exp_f32_e32 v72, v72
	v_exp_f32_e32 v73, v73
	v_exp_f32_e32 v74, v74
	v_exp_f32_e32 v75, v75
	v_exp_f32_e32 v76, v76
	v_exp_f32_e32 v77, v77
	v_exp_f32_e32 v78, v78
	v_exp_f32_e32 v79, v79
	v_add_f32_e32 v72, 1.0, v72
	v_add_f32_e32 v73, 1.0, v73
	v_add_f32_e32 v74, 1.0, v74
	v_add_f32_e32 v75, 1.0, v75
	v_add_f32_e32 v76, 1.0, v76
	v_add_f32_e32 v77, 1.0, v77
	v_add_f32_e32 v78, 1.0, v78
	v_add_f32_e32 v79, 1.0, v79
	v_rcp_f32_e32 v72, v72
	v_rcp_f32_e32 v73, v73
	v_rcp_f32_e32 v74, v74
	v_rcp_f32_e32 v75, v75
	v_rcp_f32_e32 v76, v76
	v_rcp_f32_e32 v77, v77
	v_rcp_f32_e32 v78, v78
	v_rcp_f32_e32 v79, v79
	v_mul_f32_e32 v16, v16, v72
	v_mul_f32_e32 v17, v17, v73
	v_mul_f32_e32 v18, v18, v74
	v_mul_f32_e32 v19, v19, v75
	v_mul_f32_e32 v20, v20, v76
	v_mul_f32_e32 v21, v21, v77
	v_mul_f32_e32 v22, v22, v78
	v_mul_f32_e32 v23, v23, v79
	v_mul_f32_e32 v72, 0xbfb8aa3b, v24
	v_mul_f32_e32 v73, 0xbfb8aa3b, v25
	v_mul_f32_e32 v74, 0xbfb8aa3b, v26
	v_mul_f32_e32 v75, 0xbfb8aa3b, v27
	v_mul_f32_e32 v76, 0xbfb8aa3b, v28
	v_mul_f32_e32 v77, 0xbfb8aa3b, v29
	v_mul_f32_e32 v78, 0xbfb8aa3b, v30
	v_mul_f32_e32 v79, 0xbfb8aa3b, v31
	v_exp_f32_e32 v72, v72
	v_exp_f32_e32 v73, v73
	v_exp_f32_e32 v74, v74
	v_exp_f32_e32 v75, v75
	v_exp_f32_e32 v76, v76
	v_exp_f32_e32 v77, v77
	v_exp_f32_e32 v78, v78
	v_exp_f32_e32 v79, v79
	v_add_f32_e32 v72, 1.0, v72
	v_add_f32_e32 v73, 1.0, v73
	v_add_f32_e32 v74, 1.0, v74
	v_add_f32_e32 v75, 1.0, v75
	v_add_f32_e32 v76, 1.0, v76
	v_add_f32_e32 v77, 1.0, v77
	v_add_f32_e32 v78, 1.0, v78
	v_add_f32_e32 v79, 1.0, v79
	v_rcp_f32_e32 v72, v72
	v_rcp_f32_e32 v73, v73
	v_rcp_f32_e32 v74, v74
	v_rcp_f32_e32 v75, v75
	v_rcp_f32_e32 v76, v76
	v_rcp_f32_e32 v77, v77
	v_rcp_f32_e32 v78, v78
	v_rcp_f32_e32 v79, v79
	v_mul_f32_e32 v24, v24, v72
	v_mul_f32_e32 v25, v25, v73
	v_mul_f32_e32 v26, v26, v74
	v_mul_f32_e32 v27, v27, v75
	v_mul_f32_e32 v28, v28, v76
	v_mul_f32_e32 v29, v29, v77
	v_mul_f32_e32 v30, v30, v78
	v_mul_f32_e32 v31, v31, v79
	v_mul_f32_e32 v72, 0xbfb8aa3b, v32
	v_mul_f32_e32 v73, 0xbfb8aa3b, v33
	v_mul_f32_e32 v74, 0xbfb8aa3b, v34
	v_mul_f32_e32 v75, 0xbfb8aa3b, v35
	v_mul_f32_e32 v76, 0xbfb8aa3b, v36
	v_mul_f32_e32 v77, 0xbfb8aa3b, v37
	v_mul_f32_e32 v78, 0xbfb8aa3b, v38
	v_mul_f32_e32 v79, 0xbfb8aa3b, v39
	v_exp_f32_e32 v72, v72
	v_exp_f32_e32 v73, v73
	v_exp_f32_e32 v74, v74
	v_exp_f32_e32 v75, v75
	v_exp_f32_e32 v76, v76
	v_exp_f32_e32 v77, v77
	v_exp_f32_e32 v78, v78
	v_exp_f32_e32 v79, v79
	v_add_f32_e32 v72, 1.0, v72
	v_add_f32_e32 v73, 1.0, v73
	v_add_f32_e32 v74, 1.0, v74
	v_add_f32_e32 v75, 1.0, v75
	v_add_f32_e32 v76, 1.0, v76
	v_add_f32_e32 v77, 1.0, v77
	v_add_f32_e32 v78, 1.0, v78
	v_add_f32_e32 v79, 1.0, v79
	v_rcp_f32_e32 v72, v72
	v_rcp_f32_e32 v73, v73
	v_rcp_f32_e32 v74, v74
	v_rcp_f32_e32 v75, v75
	v_rcp_f32_e32 v76, v76
	v_rcp_f32_e32 v77, v77
	v_rcp_f32_e32 v78, v78
	v_rcp_f32_e32 v79, v79
	v_mul_f32_e32 v32, v32, v72
	v_mul_f32_e32 v33, v33, v73
	v_mul_f32_e32 v34, v34, v74
	v_mul_f32_e32 v35, v35, v75
	v_mul_f32_e32 v36, v36, v76
	v_mul_f32_e32 v37, v37, v77
	v_mul_f32_e32 v38, v38, v78
	v_mul_f32_e32 v39, v39, v79
	v_mul_f32_e32 v72, 0xbfb8aa3b, v40
	v_mul_f32_e32 v73, 0xbfb8aa3b, v41
	v_mul_f32_e32 v74, 0xbfb8aa3b, v42
	v_mul_f32_e32 v75, 0xbfb8aa3b, v43
	v_mul_f32_e32 v76, 0xbfb8aa3b, v44
	v_mul_f32_e32 v77, 0xbfb8aa3b, v45
	v_mul_f32_e32 v78, 0xbfb8aa3b, v46
	v_mul_f32_e32 v79, 0xbfb8aa3b, v47
	v_exp_f32_e32 v72, v72
	v_exp_f32_e32 v73, v73
	v_exp_f32_e32 v74, v74
	v_exp_f32_e32 v75, v75
	v_exp_f32_e32 v76, v76
	v_exp_f32_e32 v77, v77
	v_exp_f32_e32 v78, v78
	v_exp_f32_e32 v79, v79
	v_add_f32_e32 v72, 1.0, v72
	v_add_f32_e32 v73, 1.0, v73
	v_add_f32_e32 v74, 1.0, v74
	v_add_f32_e32 v75, 1.0, v75
	v_add_f32_e32 v76, 1.0, v76
	v_add_f32_e32 v77, 1.0, v77
	v_add_f32_e32 v78, 1.0, v78
	v_add_f32_e32 v79, 1.0, v79
	v_rcp_f32_e32 v72, v72
	v_rcp_f32_e32 v73, v73
	v_rcp_f32_e32 v74, v74
	v_rcp_f32_e32 v75, v75
	v_rcp_f32_e32 v76, v76
	v_rcp_f32_e32 v77, v77
	v_rcp_f32_e32 v78, v78
	v_rcp_f32_e32 v79, v79
	v_mul_f32_e32 v40, v40, v72
	v_mul_f32_e32 v41, v41, v73
	v_mul_f32_e32 v42, v42, v74
	v_mul_f32_e32 v43, v43, v75
	v_mul_f32_e32 v44, v44, v76
	v_mul_f32_e32 v45, v45, v77
	v_mul_f32_e32 v46, v46, v78
	v_mul_f32_e32 v47, v47, v79
	v_mul_f32_e32 v72, 0xbfb8aa3b, v48
	v_mul_f32_e32 v73, 0xbfb8aa3b, v49
	v_mul_f32_e32 v74, 0xbfb8aa3b, v50
	v_mul_f32_e32 v75, 0xbfb8aa3b, v51
	v_mul_f32_e32 v76, 0xbfb8aa3b, v52
	v_mul_f32_e32 v77, 0xbfb8aa3b, v53
	v_mul_f32_e32 v78, 0xbfb8aa3b, v54
	v_mul_f32_e32 v79, 0xbfb8aa3b, v55
	v_exp_f32_e32 v72, v72
	v_exp_f32_e32 v73, v73
	v_exp_f32_e32 v74, v74
	v_exp_f32_e32 v75, v75
	v_exp_f32_e32 v76, v76
	v_exp_f32_e32 v77, v77
	v_exp_f32_e32 v78, v78
	v_exp_f32_e32 v79, v79
	v_add_f32_e32 v72, 1.0, v72
	v_add_f32_e32 v73, 1.0, v73
	v_add_f32_e32 v74, 1.0, v74
	v_add_f32_e32 v75, 1.0, v75
	v_add_f32_e32 v76, 1.0, v76
	v_add_f32_e32 v77, 1.0, v77
	v_add_f32_e32 v78, 1.0, v78
	v_add_f32_e32 v79, 1.0, v79
	v_rcp_f32_e32 v72, v72
	v_rcp_f32_e32 v73, v73
	v_rcp_f32_e32 v74, v74
	v_rcp_f32_e32 v75, v75
	v_rcp_f32_e32 v76, v76
	v_rcp_f32_e32 v77, v77
	v_rcp_f32_e32 v78, v78
	v_rcp_f32_e32 v79, v79
	v_mul_f32_e32 v48, v48, v72
	v_mul_f32_e32 v49, v49, v73
	v_mul_f32_e32 v50, v50, v74
	v_mul_f32_e32 v51, v51, v75
	v_mul_f32_e32 v52, v52, v76
	v_mul_f32_e32 v53, v53, v77
	v_mul_f32_e32 v54, v54, v78
	v_mul_f32_e32 v55, v55, v79
	v_mul_f32_e32 v72, 0xbfb8aa3b, v56
	v_mul_f32_e32 v73, 0xbfb8aa3b, v57
	v_mul_f32_e32 v74, 0xbfb8aa3b, v58
	v_mul_f32_e32 v75, 0xbfb8aa3b, v59
	v_mul_f32_e32 v76, 0xbfb8aa3b, v60
	v_mul_f32_e32 v77, 0xbfb8aa3b, v61
	v_mul_f32_e32 v78, 0xbfb8aa3b, v62
	v_mul_f32_e32 v79, 0xbfb8aa3b, v63
	v_exp_f32_e32 v72, v72
	v_exp_f32_e32 v73, v73
	v_exp_f32_e32 v74, v74
	v_exp_f32_e32 v75, v75
	v_exp_f32_e32 v76, v76
	v_exp_f32_e32 v77, v77
	v_exp_f32_e32 v78, v78
	v_exp_f32_e32 v79, v79
	v_add_f32_e32 v72, 1.0, v72
	v_add_f32_e32 v73, 1.0, v73
	v_add_f32_e32 v74, 1.0, v74
	v_add_f32_e32 v75, 1.0, v75
	v_add_f32_e32 v76, 1.0, v76
	v_add_f32_e32 v77, 1.0, v77
	v_add_f32_e32 v78, 1.0, v78
	v_add_f32_e32 v79, 1.0, v79
	v_rcp_f32_e32 v72, v72
	v_rcp_f32_e32 v73, v73
	v_rcp_f32_e32 v74, v74
	v_rcp_f32_e32 v75, v75
	v_rcp_f32_e32 v76, v76
	v_rcp_f32_e32 v77, v77
	v_rcp_f32_e32 v78, v78
	v_rcp_f32_e32 v79, v79
	v_mul_f32_e32 v56, v56, v72
	v_mul_f32_e32 v57, v57, v73
	v_mul_f32_e32 v58, v58, v74
	v_mul_f32_e32 v59, v59, v75
	v_mul_f32_e32 v60, v60, v76
	v_mul_f32_e32 v61, v61, v77
	v_mul_f32_e32 v62, v62, v78
	v_mul_f32_e32 v63, v63, v79
	v_mul_f32_e32 v72, 0xbfb8aa3b, v64
	v_mul_f32_e32 v73, 0xbfb8aa3b, v65
	v_mul_f32_e32 v74, 0xbfb8aa3b, v66
	v_mul_f32_e32 v75, 0xbfb8aa3b, v67
	v_mul_f32_e32 v76, 0xbfb8aa3b, v68
	v_mul_f32_e32 v77, 0xbfb8aa3b, v69
	v_mul_f32_e32 v78, 0xbfb8aa3b, v70
	v_mul_f32_e32 v79, 0xbfb8aa3b, v71
	v_exp_f32_e32 v72, v72
	v_exp_f32_e32 v73, v73
	v_exp_f32_e32 v74, v74
	v_exp_f32_e32 v75, v75
	v_exp_f32_e32 v76, v76
	v_exp_f32_e32 v77, v77
	v_exp_f32_e32 v78, v78
	v_exp_f32_e32 v79, v79
	v_add_f32_e32 v72, 1.0, v72
	v_add_f32_e32 v73, 1.0, v73
	v_add_f32_e32 v74, 1.0, v74
	v_add_f32_e32 v75, 1.0, v75
	v_add_f32_e32 v76, 1.0, v76
	v_add_f32_e32 v77, 1.0, v77
	v_add_f32_e32 v78, 1.0, v78
	v_add_f32_e32 v79, 1.0, v79
	v_rcp_f32_e32 v72, v72
	v_rcp_f32_e32 v73, v73
	v_rcp_f32_e32 v74, v74
	v_rcp_f32_e32 v75, v75
	v_rcp_f32_e32 v76, v76
	v_rcp_f32_e32 v77, v77
	v_rcp_f32_e32 v78, v78
	v_rcp_f32_e32 v79, v79
	v_mul_f32_e32 v64, v64, v72
	v_mul_f32_e32 v65, v65, v73
	v_mul_f32_e32 v66, v66, v74
	v_mul_f32_e32 v67, v67, v75
	v_mul_f32_e32 v68, v68, v76
	v_mul_f32_e32 v69, v69, v77
	v_mul_f32_e32 v70, v70, v78
	v_mul_f32_e32 v71, v71, v79
	v_lshlrev_b32_e32 v1, 2, v2
	s_lshl_b32 s6, s5, 12
	v_add_u32_e32 v121, s6, v1
	s_lshl_b32 s6, s5, 8
	v_add_u32_e32 v122, s6, v1
	s_and_b32 s6, s5, 3
	s_lshr_b32 s7, s5, 2
	s_lshl_b32 s7, s7, 3
	s_add_i32 s6, s6, s7
	v_lshl_add_u32 v123, v4, 2, s6
	v_mul_u32_u24_e32 v123, 0x6000, v123
	v_lshl_add_u32 v123, v3, 2, v123
	s_branch .Lmod_first

.Lmod_first:
	global_load_dword v177, v6, s[8:9]
	s_add_u32 s8, s8, 0x6000
	s_addc_u32 s9, s9, 0
	global_load_dword v178, v6, s[8:9]
	s_add_u32 s8, s8, 0x6000
	s_addc_u32 s9, s9, 0
	global_load_dword v179, v6, s[8:9]
	s_add_u32 s8, s8, 0x6000
	s_addc_u32 s9, s9, 0
	global_load_dword v180, v6, s[8:9]
	s_add_u32 s8, s8, 0x6000
	s_addc_u32 s9, s9, 0
	global_load_dword v181, v6, s[8:9]
	s_add_u32 s8, s8, 0x6000
	s_addc_u32 s9, s9, 0
	global_load_dword v182, v6, s[8:9]
	s_add_u32 s8, s8, 0x6000
	s_addc_u32 s9, s9, 0
	global_load_dword v183, v6, s[8:9]
	s_add_u32 s8, s8, 0x6000
	s_addc_u32 s9, s9, 0
	global_load_dword v184, v6, s[8:9]
	s_add_u32 s8, s8, 0x6000
	s_addc_u32 s9, s9, 0
	global_load_dword v185, v6, s[8:9]
	s_add_u32 s8, s8, 0x6000
	s_addc_u32 s9, s9, 0
	v_mov_b32_e32 v200, 0
	v_mov_b32_e32 v201, 0
	v_mov_b32_e32 v202, 0
	v_mov_b32_e32 v203, 0
	v_mov_b32_e32 v204, 0
	v_mov_b32_e32 v205, 0
	v_mov_b32_e32 v206, 0
	v_mov_b32_e32 v207, 0
	v_mov_b32_e32 v208, 0
	v_mov_b32_e32 v209, 0
	v_mov_b32_e32 v210, 0
	v_mov_b32_e32 v211, 0
	v_mov_b32_e32 v212, 0
	v_mov_b32_e32 v213, 0
	v_mov_b32_e32 v214, 0
	v_mov_b32_e32 v215, 0
	s_lshl_b32 s6, s4, 7
	s_add_u32 s12, s42, s6
	s_addc_u32 s13, s43, 0
	v_lshlrev_b32_e32 v124, 2, v3
	global_load_dword v125, v124, s[12:13]
	s_waitcnt vmcnt(49)
	v_mfma_f32_32x32x2_f32 v[200:215], v8, v130, v[200:215]
	v_mfma_f32_32x32x2_f32 v[200:215], v9, v131, v[200:215]
	v_mfma_f32_32x32x2_f32 v[200:215], v10, v132, v[200:215]
	v_mfma_f32_32x32x2_f32 v[200:215], v11, v133, v[200:215]
	v_mfma_f32_32x32x2_f32 v[200:215], v12, v134, v[200:215]
	v_mfma_f32_32x32x2_f32 v[200:215], v13, v135, v[200:215]
	v_mfma_f32_32x32x2_f32 v[200:215], v14, v136, v[200:215]
	v_mfma_f32_32x32x2_f32 v[200:215], v15, v137, v[200:215]
	global_load_dword v186, v6, s[8:9]
	s_add_u32 s8, s8, 0x6000
	s_addc_u32 s9, s9, 0
	global_load_dword v187, v6, s[8:9]
	s_add_u32 s8, s8, 0x6000
	s_addc_u32 s9, s9, 0
	global_load_dword v188, v6, s[8:9]
	s_add_u32 s8, s8, 0x6000
	s_addc_u32 s9, s9, 0
	global_load_dword v189, v6, s[8:9]
	s_add_u32 s8, s8, 0x6000
	s_addc_u32 s9, s9, 0
	global_load_dword v190, v6, s[8:9]
	s_add_u32 s8, s8, 0x6000
	s_addc_u32 s9, s9, 0
	global_load_dword v191, v6, s[8:9]
	s_add_u32 s8, s8, 0x6000
	s_addc_u32 s9, s9, 0
	global_load_dword v192, v6, s[8:9]
	s_add_u32 s8, s8, 0x6000
	s_addc_u32 s9, s9, 0
	global_load_dword v193, v6, s[8:9]
	s_waitcnt vmcnt(49)
	v_mfma_f32_32x32x2_f32 v[200:215], v16, v138, v[200:215]
	v_mfma_f32_32x32x2_f32 v[200:215], v17, v139, v[200:215]
	v_mfma_f32_32x32x2_f32 v[200:215], v18, v140, v[200:215]
	v_mfma_f32_32x32x2_f32 v[200:215], v19, v141, v[200:215]
	v_mfma_f32_32x32x2_f32 v[200:215], v20, v142, v[200:215]
	v_mfma_f32_32x32x2_f32 v[200:215], v21, v143, v[200:215]
	v_mfma_f32_32x32x2_f32 v[200:215], v22, v144, v[200:215]
	v_mfma_f32_32x32x2_f32 v[200:215], v23, v145, v[200:215]
	s_waitcnt vmcnt(41)
	v_mfma_f32_32x32x2_f32 v[200:215], v24, v146, v[200:215]
	v_mfma_f32_32x32x2_f32 v[200:215], v25, v147, v[200:215]
	v_mfma_f32_32x32x2_f32 v[200:215], v26, v148, v[200:215]
	v_mfma_f32_32x32x2_f32 v[200:215], v27, v149, v[200:215]
	v_mfma_f32_32x32x2_f32 v[200:215], v28, v150, v[200:215]
	v_mfma_f32_32x32x2_f32 v[200:215], v29, v151, v[200:215]
	v_mfma_f32_32x32x2_f32 v[200:215], v30, v152, v[200:215]
	v_mfma_f32_32x32x2_f32 v[200:215], v31, v153, v[200:215]
	s_waitcnt vmcnt(33)
	v_mfma_f32_32x32x2_f32 v[200:215], v32, v154, v[200:215]
	v_mfma_f32_32x32x2_f32 v[200:215], v33, v155, v[200:215]
	v_mfma_f32_32x32x2_f32 v[200:215], v34, v156, v[200:215]
	v_mfma_f32_32x32x2_f32 v[200:215], v35, v157, v[200:215]
	v_mfma_f32_32x32x2_f32 v[200:215], v36, v158, v[200:215]
	v_mfma_f32_32x32x2_f32 v[200:215], v37, v159, v[200:215]
	v_mfma_f32_32x32x2_f32 v[200:215], v38, v160, v[200:215]
	v_mfma_f32_32x32x2_f32 v[200:215], v39, v161, v[200:215]
	s_waitcnt vmcnt(25)
	v_mfma_f32_32x32x2_f32 v[200:215], v40, v162, v[200:215]
	v_mfma_f32_32x32x2_f32 v[200:215], v41, v163, v[200:215]
	v_mfma_f32_32x32x2_f32 v[200:215], v42, v164, v[200:215]
	v_mfma_f32_32x32x2_f32 v[200:215], v43, v165, v[200:215]
	v_mfma_f32_32x32x2_f32 v[200:215], v44, v166, v[200:215]
	v_mfma_f32_32x32x2_f32 v[200:215], v45, v167, v[200:215]
	v_mfma_f32_32x32x2_f32 v[200:215], v46, v168, v[200:215]
	v_mfma_f32_32x32x2_f32 v[200:215], v47, v169, v[200:215]
	s_waitcnt vmcnt(17)
	v_mfma_f32_32x32x2_f32 v[200:215], v48, v170, v[200:215]
	v_mfma_f32_32x32x2_f32 v[200:215], v49, v171, v[200:215]
	v_mfma_f32_32x32x2_f32 v[200:215], v50, v172, v[200:215]
	v_mfma_f32_32x32x2_f32 v[200:215], v51, v173, v[200:215]
	v_mfma_f32_32x32x2_f32 v[200:215], v52, v174, v[200:215]
	v_mfma_f32_32x32x2_f32 v[200:215], v53, v175, v[200:215]
	v_mfma_f32_32x32x2_f32 v[200:215], v54, v176, v[200:215]
	v_mfma_f32_32x32x2_f32 v[200:215], v55, v177, v[200:215]
	s_waitcnt vmcnt(9)
	v_mfma_f32_32x32x2_f32 v[200:215], v56, v178, v[200:215]
	v_mfma_f32_32x32x2_f32 v[200:215], v57, v179, v[200:215]
	v_mfma_f32_32x32x2_f32 v[200:215], v58, v180, v[200:215]
	v_mfma_f32_32x32x2_f32 v[200:215], v59, v181, v[200:215]
	v_mfma_f32_32x32x2_f32 v[200:215], v60, v182, v[200:215]
	v_mfma_f32_32x32x2_f32 v[200:215], v61, v183, v[200:215]
	v_mfma_f32_32x32x2_f32 v[200:215], v62, v184, v[200:215]
	v_mfma_f32_32x32x2_f32 v[200:215], v63, v185, v[200:215]
	s_waitcnt vmcnt(0)
	v_mfma_f32_32x32x2_f32 v[200:215], v64, v186, v[200:215]
	v_mfma_f32_32x32x2_f32 v[200:215], v65, v187, v[200:215]
	v_mfma_f32_32x32x2_f32 v[200:215], v66, v188, v[200:215]
	v_mfma_f32_32x32x2_f32 v[200:215], v67, v189, v[200:215]
	v_mfma_f32_32x32x2_f32 v[200:215], v68, v190, v[200:215]
	v_mfma_f32_32x32x2_f32 v[200:215], v69, v191, v[200:215]
	v_mfma_f32_32x32x2_f32 v[200:215], v70, v192, v[200:215]
	v_mfma_f32_32x32x2_f32 v[200:215], v71, v193, v[200:215]
	s_nop 15
	s_nop 3
	ds_write_b32 v121, v200 offset:0
	ds_write_b32 v121, v201 offset:256
	ds_write_b32 v121, v202 offset:512
	ds_write_b32 v121, v203 offset:768
	ds_write_b32 v121, v204 offset:1024
	ds_write_b32 v121, v205 offset:1280
	ds_write_b32 v121, v206 offset:1536
	ds_write_b32 v121, v207 offset:1792
	ds_write_b32 v121, v208 offset:2048
	ds_write_b32 v121, v209 offset:2304
	ds_write_b32 v121, v210 offset:2560
	ds_write_b32 v121, v211 offset:2816
	ds_write_b32 v121, v212 offset:3072
	ds_write_b32 v121, v213 offset:3328
	ds_write_b32 v121, v214 offset:3584
	ds_write_b32 v121, v215 offset:3840
	s_waitcnt lgkmcnt(0)
	s_barrier
	ds_read_b32 v72, v122 offset:0
	ds_read_b32 v73, v122 offset:4096
	ds_read_b32 v74, v122 offset:8192
	ds_read_b32 v75, v122 offset:12288
	ds_read_b32 v76, v122 offset:16384
	ds_read_b32 v77, v122 offset:20480
	ds_read_b32 v78, v122 offset:24576
	ds_read_b32 v79, v122 offset:28672
	ds_read_b32 v80, v122 offset:2048
	ds_read_b32 v81, v122 offset:6144
	ds_read_b32 v82, v122 offset:10240
	ds_read_b32 v83, v122 offset:14336
	ds_read_b32 v84, v122 offset:18432
	ds_read_b32 v85, v122 offset:22528
	ds_read_b32 v86, v122 offset:26624
	ds_read_b32 v87, v122 offset:30720
	s_waitcnt lgkmcnt(8)
	v_add_f32_e32 v72, v72, v73
	v_add_f32_e32 v72, v72, v74
	v_add_f32_e32 v72, v72, v75
	v_add_f32_e32 v72, v72, v76
	v_add_f32_e32 v72, v72, v77
	v_add_f32_e32 v72, v72, v78
	v_add_f32_e32 v72, v72, v79
	s_waitcnt lgkmcnt(0)
	v_add_f32_e32 v80, v80, v81
	v_add_f32_e32 v80, v80, v82
	v_add_f32_e32 v80, v80, v83
	v_add_f32_e32 v80, v80, v84
	v_add_f32_e32 v80, v80, v85
	v_add_f32_e32 v80, v80, v86
	v_add_f32_e32 v80, v80, v87
	s_waitcnt vmcnt(0)
	v_add_f32_e32 v72, v72, v125
	v_add_f32_e32 v80, v80, v125
	s_lshl_b32 s6, s4, 7
	s_add_u32 s12, s68, s6
	s_addc_u32 s13, s69, 0
	global_store_dword v123, v72, s[12:13]
	s_add_u32 s12, s12, 0x60000
	s_addc_u32 s13, s13, 0
	global_store_dword v123, v80, s[12:13]
	s_add_i32 s4, s4, s3
	s_cmpk_gt_i32 s4, 0xbf
	s_barrier
	s_cbranch_scc0 .Lmod_item
